# S epilogue: gate_s loaded in the prologue, merged S output written straight into sO (the dummy second merge and its gate reload are bypassed), first sliding-window tile loaded into the spare staging s
# baseline (speedup 1.0000x reference)
.LBB0_2164:
	s_or_b64 exec, exec, s[20:21]
	v_add_u32_e32 v38, v34, v35
	v_bcnt_u32_b32 v37, v37, 0
	v_add_u32_e32 v38, v38, v36
	v_add_u32_e32 v150, v38, v37
	v_mul_f32_e32 v38, v133, v146
	v_cmp_eq_u32_e32 vcc, 0, v150
	v_pk_mul_f32 v[82:83], v[38:39], v[18:19] op_sel_hi:[0,1]
	v_add_u32_e32 v215, 0x9000, v214
	v_pk_mul_f32 v[84:85], v[38:39], v[20:21] op_sel_hi:[0,1]
	v_add_u32_e32 v216, 0x9008, v214
	v_pk_mul_f32 v[86:87], v[38:39], v[22:23] op_sel_hi:[0,1]
	v_add_u32_e32 v217, 0x9020, v214
	v_pk_mul_f32 v[88:89], v[38:39], v[24:25] op_sel_hi:[0,1]
	v_add_u32_e32 v218, 0x9028, v214
	v_pk_mul_f32 v[90:91], v[38:39], v[26:27] op_sel_hi:[0,1]
	v_add_u32_e32 v219, 0x9040, v214
	v_pk_mul_f32 v[92:93], v[38:39], v[28:29] op_sel_hi:[0,1]
	v_add_u32_e32 v220, 0x9048, v214
	v_pk_mul_f32 v[94:95], v[38:39], v[30:31] op_sel_hi:[0,1]
	v_add_u32_e32 v221, 0x9060, v214
	v_pk_mul_f32 v[96:97], v[38:39], v[32:33] op_sel_hi:[0,1]
	v_add_u32_e32 v222, 0x9068, v214
	v_pk_mul_f32 v[134:135], v[38:39], v[2:3] op_sel_hi:[0,1]
	v_add_u32_e32 v223, 0x9080, v214
	v_pk_mul_f32 v[136:137], v[38:39], v[4:5] op_sel_hi:[0,1]
	v_add_u32_e32 v224, 0x9088, v214
	v_pk_mul_f32 v[138:139], v[38:39], v[6:7] op_sel_hi:[0,1]
	v_add_u32_e32 v225, 0x90a0, v214
	v_pk_mul_f32 v[140:141], v[38:39], v[8:9] op_sel_hi:[0,1]
	v_add_u32_e32 v226, 0x90a8, v214
	v_pk_mul_f32 v[142:143], v[38:39], v[10:11] op_sel_hi:[0,1]
	v_add_u32_e32 v227, 0x90c0, v214
	v_pk_mul_f32 v[144:145], v[38:39], v[12:13] op_sel_hi:[0,1]
	v_add_u32_e32 v228, 0x90c8, v214
	v_pk_mul_f32 v[146:147], v[38:39], v[14:15] op_sel_hi:[0,1]
	v_add_u32_e32 v229, 0x90e0, v214
	v_pk_mul_f32 v[148:149], v[38:39], v[16:17] op_sel_hi:[0,1]
	v_add_u32_e32 v230, 0x90e8, v214
	s_and_b64 vcc, exec, vcc
	s_lshl_b32 s24, s71, 19
	s_waitcnt lgkmcnt(0)
	s_barrier
	ds_write2_b32 v215, v82, v83 offset1:1
	ds_write2_b32 v216, v84, v85 offset1:1
	ds_write2_b32 v217, v86, v87 offset1:1
	ds_write2_b32 v218, v88, v89 offset1:1
	ds_write2_b32 v219, v90, v91 offset1:1
	ds_write2_b32 v220, v92, v93 offset1:1
	ds_write2_b32 v221, v94, v95 offset1:1
	ds_write2_b32 v222, v96, v97 offset1:1
	ds_write2_b32 v223, v134, v135 offset1:1
	ds_write2_b32 v224, v136, v137 offset1:1
	ds_write2_b32 v225, v138, v139 offset1:1
	ds_write2_b32 v226, v140, v141 offset1:1
	ds_write2_b32 v227, v142, v143 offset1:1
	ds_write2_b32 v228, v144, v145 offset1:1
	ds_write2_b32 v229, v146, v147 offset1:1
	ds_write2_b32 v230, v148, v149 offset1:1
	s_cbranch_vccnz .LBB0_2181
	s_lshl_b32 s96, s66, 12
	s_and_b32 s96, s96, 0x6000
	s_lshl_b32 s95, s66, 3
	s_and_b32 s95, s95, 8
	s_sub_i32 s94, 0x1ff0, s70
	s_mov_b32 s98, 0x1000
	s_mov_b32 s99, 0
	v_and_b32_e32 v40, 15, v166
	v_bfe_u32 v41, v166, 4, 2
	v_lshrrev_b32_e32 v42, 6, v166
	v_lshlrev_b32_e32 v36, 4, v42
	v_and_b32_e32 v37, 63, v166
	v_readfirstlane_b32 s86, v36
	s_lshr_b32 s86, s86, 2
	s_lshl_b32 s87, 12, s86
	s_lshl_b32 s86, 3, s86
	v_lshlrev_b32_e32 v37, 2, v37
	v_add_u32_e32 v37, 0x11200, v37
	ds_read_b32 v133, v37 offset:256
	ds_read_b32 v148, v37 offset:512
	v_mul_u32_u24_e32 v234, 0x90, v40
	v_lshl_add_u32 v234, v41, 4, v234
	v_bfe_u32 v43, v166, 3, 1
	v_lshl_add_u32 v43, v42, 2, v43
	v_add_u32_e32 v236, s94, v43
	v_lshlrev_b32_e32 v44, 2, v41
	v_sub_u32_e32 v239, v236, v44
	v_lshl_add_u32 v45, v42, 5, v40
	v_mul_u32_u24_e32 v45, 0x41, v45
	v_lshl_add_u32 v45, v41, 2, v45
	v_lshlrev_b32_e32 v45, 2, v45
	v_add_u32_e32 v237, 0x9000, v45
	v_add_u32_e32 v238, 0x1040, v237
	v_add_u32_e32 v46, s96, v236
	v_mov_b32_e32 v47, 0
	v_lshlrev_b64 v[46:47], 11, v[46:47]
	v_lshl_add_u64 v[46:47], s[42:43], 0, v[46:47]
	v_and_b32_e32 v48, 7, v166
	v_or_b32_e32 v48, s95, v48
	v_lshlrev_b32_e32 v48, 7, v48
	v_lshl_add_u32 v48, v41, 4, v48
	v_mov_b32_e32 v49, 0
	v_lshl_add_u64 v[46:47], v[46:47], 0, v[48:49]
	global_load_dwordx4 v[66:69], v[46:47], off
	global_load_dwordx4 v[70:73], v[46:47], off offset:64
	v_lshl_add_u64 v[48:49], v[46:47], 0, s[98:99]
	global_load_dwordx4 v[74:77], v[48:49], off
	global_load_dwordx4 v[78:81], v[48:49], off offset:64
	v_mov_b32_e32 v235, 0
	v_add_u32_e32 v46, s96, v236
	v_mov_b32_e32 v47, 0xc0
	v_mad_u64_u32 v[38:39], s[98:99], v46, v47, v[124:125]
	v_and_b32_e32 v48, 7, v166
	v_or_b32_e32 v48, s95, v48
	v_lshlrev_b32_e32 v48, 2, v48
	v_mov_b32_e32 v49, 0
	v_lshl_add_u64 v[38:39], v[38:39], 0, v[48:49]
	global_load_dword v149, v[38:39], off offset:64
	global_load_dword v147, v[38:39], off offset:448
	s_lshl_b32 s22, s24, 1
	v_readlane_b32 s20, v231, 14
	s_add_u32 s20, s20, s22
	v_readlane_b32 s21, v231, 10
	s_addc_u32 s21, s21, 0
	s_add_u32 s22, s52, s22
	s_addc_u32 s23, s53, 0
	v_add_u32_e32 v134, v128, v106
	v_add_u32_e32 v135, v128, v108
	v_readfirstlane_b32 s101, v150
	s_mov_b32 s25, 0
	s_waitcnt lgkmcnt(0)
	s_and_b32 s38, s25, 63
	v_readlane_b32 s32, v133, s38
	v_readlane_b32 s38, v148, s38
	s_bitcmp1_b32 s25, 6
	s_cselect_b32 s32, s38, s32
	s_lshl_b32 s32, s32, 13
	s_add_u32 s28, s20, s32
	s_addc_u32 s29, s21, 0
	s_add_u32 s82, s22, s32
	s_addc_u32 s83, s23, 0
	global_load_dwordx4 v[82:85], v134, s[28:29]
	global_load_dwordx4 v[86:89], v134, s[82:83]
	global_load_dwordx4 v[90:93], v135, s[28:29]
	global_load_dwordx4 v[94:97], v135, s[82:83]
	s_cmp_lt_u32 s101, 2
	s_cbranch_scc1 .Lsb16_pa
	s_mov_b32 s58, 1
	s_and_b32 s38, s58, 63
	v_readlane_b32 s32, v133, s38
	v_readlane_b32 s38, v148, s38
	s_bitcmp1_b32 s58, 6
	s_cselect_b32 s32, s38, s32
	s_lshl_b32 s32, s32, 13
	s_add_u32 s28, s20, s32
	s_addc_u32 s29, s21, 0
	s_add_u32 s82, s22, s32
	s_addc_u32 s83, s23, 0
	global_load_dwordx4 v[240:243], v134, s[28:29]
	global_load_dwordx4 v[244:247], v134, s[82:83]
	global_load_dwordx4 v[248:251], v135, s[28:29]
	global_load_dwordx4 v[252:255], v135, s[82:83]

.Lsb16_nost_0:
	s_and_b32 s38, s25, 63
	v_readlane_b32 s32, v136, s38
	v_readlane_b32 s38, v137, s38
	s_bitcmp1_b32 s25, 6
	s_cselect_b32 s77, s38, s32
	s_and_b32 s56, s77, s86
	s_and_b32 s57, s77, s87
	s_or_b32 s28, s56, s57
	s_cmp_eq_u32 s28, 0
	s_cbranch_scc1 .Lsb16_end_0
	s_and_b32 s38, s25, 63
	v_readlane_b32 s32, v133, s38
	v_readlane_b32 s38, v148, s38
	s_bitcmp1_b32 s25, 6
	s_cselect_b32 s76, s38, s32
	s_cmp_eq_u32 s56, 0
	s_cbranch_scc1 .Lsb16_g1_0
	ds_read_b128 v[50:53], v234
	ds_read_b128 v[54:57], v234 offset:64
	ds_read_b128 v[58:61], v234 offset:2304
	ds_read_b128 v[62:65], v234 offset:2368
	ds_read_b128 v[138:141], v234 offset:4608
	ds_read_b128 v[142:145], v234 offset:4672
	v_subrev_u32_e32 v146, s94, v236
	v_lshrrev_b32_e64 v146, v146, s77
	v_and_b32_e32 v146, 1, v146
	v_cmp_ne_u32_e32 vcc, 0, v146
	s_nop 1
	v_cndmask_b32_e32 v146, v213, v100, vcc
	s_waitcnt lgkmcnt(5)
	v_mfma_f32_16x16x32_bf16 v[34:37], v[50:53], v[66:69], 0
	s_waitcnt lgkmcnt(4)
	v_mfma_f32_16x16x32_bf16 v[34:37], v[54:57], v[70:73], v[34:37]
	ds_read_b128 v[50:53], v234 offset:6912
	ds_read_b128 v[54:57], v234 offset:6976
	s_waitcnt lgkmcnt(5)
	v_mfma_f32_16x16x32_bf16 v[38:41], v[58:61], v[66:69], 0
	s_waitcnt lgkmcnt(4)
	v_mfma_f32_16x16x32_bf16 v[38:41], v[62:65], v[70:73], v[38:41]
	ds_read_b128 v[58:61], v234 offset:9216
	ds_read_b128 v[62:65], v234 offset:9280
	s_waitcnt lgkmcnt(5)
	v_mfma_f32_16x16x32_bf16 v[42:45], v[138:141], v[66:69], 0
	s_waitcnt lgkmcnt(4)
	v_mfma_f32_16x16x32_bf16 v[42:45], v[142:145], v[70:73], v[42:45]
	s_waitcnt lgkmcnt(3)
	v_mfma_f32_16x16x32_bf16 v[46:49], v[50:53], v[66:69], 0
	s_waitcnt lgkmcnt(2)
	v_mfma_f32_16x16x32_bf16 v[46:49], v[54:57], v[70:73], v[46:49]
	ds_read_b128 v[50:53], v234 offset:11520
	ds_read_b128 v[54:57], v234 offset:11584
	v_fma_f32 v34, v34, s48, v146
	v_fma_f32 v35, v35, s48, v146
	v_fma_f32 v36, v36, s48, v146
	v_fma_f32 v37, v37, s48, v146
	v_fma_f32 v38, v38, s48, v146
	v_fma_f32 v39, v39, s48, v146
	v_fma_f32 v40, v40, s48, v146
	v_fma_f32 v41, v41, s48, v146
	v_fma_f32 v42, v42, s48, v146
	v_fma_f32 v43, v43, s48, v146
	v_fma_f32 v44, v44, s48, v146
	v_fma_f32 v45, v45, s48, v146
	v_fma_f32 v46, v46, s48, v146
	v_fma_f32 v47, v47, s48, v146
	v_fma_f32 v48, v48, s48, v146
	v_fma_f32 v49, v49, s48, v146
	s_cmp_lg_u32 s76, s72
	s_cbranch_scc1 .Lsb16_nm0_0
	s_lshl_b32 s83, s76, 6
	v_subrev_u32_e32 v146, s83, v239
	v_cmp_le_i32_e64 s[28:29], 0, v146
	s_nop 1
	v_cndmask_b32_e64 v34, v213, v34, s[28:29]
	v_cmp_le_i32_e64 s[28:29], 1, v146
	s_nop 1
	v_cndmask_b32_e64 v35, v213, v35, s[28:29]
	v_cmp_le_i32_e64 s[28:29], 2, v146
	s_nop 1
	v_cndmask_b32_e64 v36, v213, v36, s[28:29]
	v_cmp_le_i32_e64 s[28:29], 3, v146
	s_nop 1
	v_cndmask_b32_e64 v37, v213, v37, s[28:29]
	v_cmp_le_i32_e64 s[28:29], 16, v146
	s_nop 1
	v_cndmask_b32_e64 v38, v213, v38, s[28:29]
	v_cmp_le_i32_e64 s[28:29], 17, v146
	s_nop 1
	v_cndmask_b32_e64 v39, v213, v39, s[28:29]
	v_cmp_le_i32_e64 s[28:29], 18, v146
	s_nop 1
	v_cndmask_b32_e64 v40, v213, v40, s[28:29]
	v_cmp_le_i32_e64 s[28:29], 19, v146
	s_nop 1
	v_cndmask_b32_e64 v41, v213, v41, s[28:29]
	v_cmp_le_i32_e64 s[28:29], 32, v146
	s_nop 1
	v_cndmask_b32_e64 v42, v213, v42, s[28:29]
	v_cmp_le_i32_e64 s[28:29], 33, v146
	s_nop 1
	v_cndmask_b32_e64 v43, v213, v43, s[28:29]
	v_cmp_le_i32_e64 s[28:29], 34, v146
	s_nop 1
	v_cndmask_b32_e64 v44, v213, v44, s[28:29]
	v_cmp_le_i32_e64 s[28:29], 35, v146
	s_nop 1
	v_cndmask_b32_e64 v45, v213, v45, s[28:29]
	v_cmp_le_i32_e64 s[28:29], 48, v146
	s_nop 1
	v_cndmask_b32_e64 v46, v213, v46, s[28:29]
	v_cmp_le_i32_e64 s[28:29], 49, v146
	s_nop 1
	v_cndmask_b32_e64 v47, v213, v47, s[28:29]
	v_cmp_le_i32_e64 s[28:29], 50, v146
	s_nop 1
	v_cndmask_b32_e64 v48, v213, v48, s[28:29]
	v_cmp_le_i32_e64 s[28:29], 51, v146
	s_nop 1
	v_cndmask_b32_e64 v49, v213, v49, s[28:29]

.Lsb16_g1_0:
	s_cmp_eq_u32 s57, 0
	s_cbranch_scc1 .Lsb16_end_0
	ds_read_b128 v[50:53], v234
	ds_read_b128 v[54:57], v234 offset:64
	ds_read_b128 v[58:61], v234 offset:2304
	ds_read_b128 v[62:65], v234 offset:2368
	ds_read_b128 v[138:141], v234 offset:4608
	ds_read_b128 v[142:145], v234 offset:4672
	v_subrev_u32_e32 v146, s94, v236
	v_add_u32_e32 v146, 2, v146
	v_lshrrev_b32_e64 v146, v146, s77
	v_and_b32_e32 v146, 1, v146
	v_cmp_ne_u32_e32 vcc, 0, v146
	s_nop 1
	v_cndmask_b32_e32 v146, v213, v100, vcc
	s_waitcnt lgkmcnt(5)
	v_mfma_f32_16x16x32_bf16 v[34:37], v[50:53], v[74:77], 0
	s_waitcnt lgkmcnt(4)
	v_mfma_f32_16x16x32_bf16 v[34:37], v[54:57], v[78:81], v[34:37]
	ds_read_b128 v[50:53], v234 offset:6912
	ds_read_b128 v[54:57], v234 offset:6976
	s_waitcnt lgkmcnt(5)
	v_mfma_f32_16x16x32_bf16 v[38:41], v[58:61], v[74:77], 0
	s_waitcnt lgkmcnt(4)
	v_mfma_f32_16x16x32_bf16 v[38:41], v[62:65], v[78:81], v[38:41]
	ds_read_b128 v[58:61], v234 offset:9216
	ds_read_b128 v[62:65], v234 offset:9280
	s_waitcnt lgkmcnt(5)
	v_mfma_f32_16x16x32_bf16 v[42:45], v[138:141], v[74:77], 0
	s_waitcnt lgkmcnt(4)
	v_mfma_f32_16x16x32_bf16 v[42:45], v[142:145], v[78:81], v[42:45]
	s_waitcnt lgkmcnt(3)
	v_mfma_f32_16x16x32_bf16 v[46:49], v[50:53], v[74:77], 0
	s_waitcnt lgkmcnt(2)
	v_mfma_f32_16x16x32_bf16 v[46:49], v[54:57], v[78:81], v[46:49]
	ds_read_b128 v[50:53], v234 offset:11520
	ds_read_b128 v[54:57], v234 offset:11584
	v_fma_f32 v34, v34, s48, v146
	v_fma_f32 v35, v35, s48, v146
	v_fma_f32 v36, v36, s48, v146
	v_fma_f32 v37, v37, s48, v146
	v_fma_f32 v38, v38, s48, v146
	v_fma_f32 v39, v39, s48, v146
	v_fma_f32 v40, v40, s48, v146
	v_fma_f32 v41, v41, s48, v146
	v_fma_f32 v42, v42, s48, v146
	v_fma_f32 v43, v43, s48, v146
	v_fma_f32 v44, v44, s48, v146
	v_fma_f32 v45, v45, s48, v146
	v_fma_f32 v46, v46, s48, v146
	v_fma_f32 v47, v47, s48, v146
	v_fma_f32 v48, v48, s48, v146
	v_fma_f32 v49, v49, s48, v146
	s_cmp_lg_u32 s76, s72
	s_cbranch_scc1 .Lsb16_nm1_0
	s_lshl_b32 s83, s76, 6
	v_subrev_u32_e32 v146, s83, v239
	v_add_u32_e32 v146, 2, v146
	v_cmp_le_i32_e64 s[28:29], 0, v146
	s_nop 1
	v_cndmask_b32_e64 v34, v213, v34, s[28:29]
	v_cmp_le_i32_e64 s[28:29], 1, v146
	s_nop 1
	v_cndmask_b32_e64 v35, v213, v35, s[28:29]
	v_cmp_le_i32_e64 s[28:29], 2, v146
	s_nop 1
	v_cndmask_b32_e64 v36, v213, v36, s[28:29]
	v_cmp_le_i32_e64 s[28:29], 3, v146
	s_nop 1
	v_cndmask_b32_e64 v37, v213, v37, s[28:29]
	v_cmp_le_i32_e64 s[28:29], 16, v146
	s_nop 1
	v_cndmask_b32_e64 v38, v213, v38, s[28:29]
	v_cmp_le_i32_e64 s[28:29], 17, v146
	s_nop 1
	v_cndmask_b32_e64 v39, v213, v39, s[28:29]
	v_cmp_le_i32_e64 s[28:29], 18, v146
	s_nop 1
	v_cndmask_b32_e64 v40, v213, v40, s[28:29]
	v_cmp_le_i32_e64 s[28:29], 19, v146
	s_nop 1
	v_cndmask_b32_e64 v41, v213, v41, s[28:29]
	v_cmp_le_i32_e64 s[28:29], 32, v146
	s_nop 1
	v_cndmask_b32_e64 v42, v213, v42, s[28:29]
	v_cmp_le_i32_e64 s[28:29], 33, v146
	s_nop 1
	v_cndmask_b32_e64 v43, v213, v43, s[28:29]
	v_cmp_le_i32_e64 s[28:29], 34, v146
	s_nop 1
	v_cndmask_b32_e64 v44, v213, v44, s[28:29]
	v_cmp_le_i32_e64 s[28:29], 35, v146
	s_nop 1
	v_cndmask_b32_e64 v45, v213, v45, s[28:29]
	v_cmp_le_i32_e64 s[28:29], 48, v146
	s_nop 1
	v_cndmask_b32_e64 v46, v213, v46, s[28:29]
	v_cmp_le_i32_e64 s[28:29], 49, v146
	s_nop 1
	v_cndmask_b32_e64 v47, v213, v47, s[28:29]
	v_cmp_le_i32_e64 s[28:29], 50, v146
	s_nop 1
	v_cndmask_b32_e64 v48, v213, v48, s[28:29]
	v_cmp_le_i32_e64 s[28:29], 51, v146
	s_nop 1
	v_cndmask_b32_e64 v49, v213, v49, s[28:29]

.Lsb16_nost_1:
	s_and_b32 s38, s25, 63
	v_readlane_b32 s32, v136, s38
	v_readlane_b32 s38, v137, s38
	s_bitcmp1_b32 s25, 6
	s_cselect_b32 s77, s38, s32
	s_and_b32 s56, s77, s86
	s_and_b32 s57, s77, s87
	s_or_b32 s28, s56, s57
	s_cmp_eq_u32 s28, 0
	s_cbranch_scc1 .Lsb16_end_1
	s_and_b32 s38, s25, 63
	v_readlane_b32 s32, v133, s38
	v_readlane_b32 s38, v148, s38
	s_bitcmp1_b32 s25, 6
	s_cselect_b32 s76, s38, s32
	s_cmp_eq_u32 s56, 0
	s_cbranch_scc1 .Lsb16_g1_1
	ds_read_b128 v[50:53], v234 offset:18432
	ds_read_b128 v[54:57], v234 offset:18496
	ds_read_b128 v[58:61], v234 offset:20736
	ds_read_b128 v[62:65], v234 offset:20800
	ds_read_b128 v[138:141], v234 offset:23040
	ds_read_b128 v[142:145], v234 offset:23104
	v_subrev_u32_e32 v146, s94, v236
	v_lshrrev_b32_e64 v146, v146, s77
	v_and_b32_e32 v146, 1, v146
	v_cmp_ne_u32_e32 vcc, 0, v146
	s_nop 1
	v_cndmask_b32_e32 v146, v213, v100, vcc
	s_waitcnt lgkmcnt(5)
	v_mfma_f32_16x16x32_bf16 v[34:37], v[50:53], v[66:69], 0
	s_waitcnt lgkmcnt(4)
	v_mfma_f32_16x16x32_bf16 v[34:37], v[54:57], v[70:73], v[34:37]
	ds_read_b128 v[50:53], v234 offset:25344
	ds_read_b128 v[54:57], v234 offset:25408
	s_waitcnt lgkmcnt(5)
	v_mfma_f32_16x16x32_bf16 v[38:41], v[58:61], v[66:69], 0
	s_waitcnt lgkmcnt(4)
	v_mfma_f32_16x16x32_bf16 v[38:41], v[62:65], v[70:73], v[38:41]
	ds_read_b128 v[58:61], v234 offset:27648
	ds_read_b128 v[62:65], v234 offset:27712
	s_waitcnt lgkmcnt(5)
	v_mfma_f32_16x16x32_bf16 v[42:45], v[138:141], v[66:69], 0
	s_waitcnt lgkmcnt(4)
	v_mfma_f32_16x16x32_bf16 v[42:45], v[142:145], v[70:73], v[42:45]
	s_waitcnt lgkmcnt(3)
	v_mfma_f32_16x16x32_bf16 v[46:49], v[50:53], v[66:69], 0
	s_waitcnt lgkmcnt(2)
	v_mfma_f32_16x16x32_bf16 v[46:49], v[54:57], v[70:73], v[46:49]
	ds_read_b128 v[50:53], v234 offset:29952
	ds_read_b128 v[54:57], v234 offset:30016
	v_fma_f32 v34, v34, s48, v146
	v_fma_f32 v35, v35, s48, v146
	v_fma_f32 v36, v36, s48, v146
	v_fma_f32 v37, v37, s48, v146
	v_fma_f32 v38, v38, s48, v146
	v_fma_f32 v39, v39, s48, v146
	v_fma_f32 v40, v40, s48, v146
	v_fma_f32 v41, v41, s48, v146
	v_fma_f32 v42, v42, s48, v146
	v_fma_f32 v43, v43, s48, v146
	v_fma_f32 v44, v44, s48, v146
	v_fma_f32 v45, v45, s48, v146
	v_fma_f32 v46, v46, s48, v146
	v_fma_f32 v47, v47, s48, v146
	v_fma_f32 v48, v48, s48, v146
	v_fma_f32 v49, v49, s48, v146
	s_cmp_lg_u32 s76, s72
	s_cbranch_scc1 .Lsb16_nm0_1
	s_lshl_b32 s83, s76, 6
	v_subrev_u32_e32 v146, s83, v239
	v_cmp_le_i32_e64 s[28:29], 0, v146
	s_nop 1
	v_cndmask_b32_e64 v34, v213, v34, s[28:29]
	v_cmp_le_i32_e64 s[28:29], 1, v146
	s_nop 1
	v_cndmask_b32_e64 v35, v213, v35, s[28:29]
	v_cmp_le_i32_e64 s[28:29], 2, v146
	s_nop 1
	v_cndmask_b32_e64 v36, v213, v36, s[28:29]
	v_cmp_le_i32_e64 s[28:29], 3, v146
	s_nop 1
	v_cndmask_b32_e64 v37, v213, v37, s[28:29]
	v_cmp_le_i32_e64 s[28:29], 16, v146
	s_nop 1
	v_cndmask_b32_e64 v38, v213, v38, s[28:29]
	v_cmp_le_i32_e64 s[28:29], 17, v146
	s_nop 1
	v_cndmask_b32_e64 v39, v213, v39, s[28:29]
	v_cmp_le_i32_e64 s[28:29], 18, v146
	s_nop 1
	v_cndmask_b32_e64 v40, v213, v40, s[28:29]
	v_cmp_le_i32_e64 s[28:29], 19, v146
	s_nop 1
	v_cndmask_b32_e64 v41, v213, v41, s[28:29]
	v_cmp_le_i32_e64 s[28:29], 32, v146
	s_nop 1
	v_cndmask_b32_e64 v42, v213, v42, s[28:29]
	v_cmp_le_i32_e64 s[28:29], 33, v146
	s_nop 1
	v_cndmask_b32_e64 v43, v213, v43, s[28:29]
	v_cmp_le_i32_e64 s[28:29], 34, v146
	s_nop 1
	v_cndmask_b32_e64 v44, v213, v44, s[28:29]
	v_cmp_le_i32_e64 s[28:29], 35, v146
	s_nop 1
	v_cndmask_b32_e64 v45, v213, v45, s[28:29]
	v_cmp_le_i32_e64 s[28:29], 48, v146
	s_nop 1
	v_cndmask_b32_e64 v46, v213, v46, s[28:29]
	v_cmp_le_i32_e64 s[28:29], 49, v146
	s_nop 1
	v_cndmask_b32_e64 v47, v213, v47, s[28:29]
	v_cmp_le_i32_e64 s[28:29], 50, v146
	s_nop 1
	v_cndmask_b32_e64 v48, v213, v48, s[28:29]
	v_cmp_le_i32_e64 s[28:29], 51, v146
	s_nop 1
	v_cndmask_b32_e64 v49, v213, v49, s[28:29]

.Lsb16_g1_1:
	s_cmp_eq_u32 s57, 0
	s_cbranch_scc1 .Lsb16_end_1
	ds_read_b128 v[50:53], v234 offset:18432
	ds_read_b128 v[54:57], v234 offset:18496
	ds_read_b128 v[58:61], v234 offset:20736
	ds_read_b128 v[62:65], v234 offset:20800
	ds_read_b128 v[138:141], v234 offset:23040
	ds_read_b128 v[142:145], v234 offset:23104
	v_subrev_u32_e32 v146, s94, v236
	v_add_u32_e32 v146, 2, v146
	v_lshrrev_b32_e64 v146, v146, s77
	v_and_b32_e32 v146, 1, v146
	v_cmp_ne_u32_e32 vcc, 0, v146
	s_nop 1
	v_cndmask_b32_e32 v146, v213, v100, vcc
	s_waitcnt lgkmcnt(5)
	v_mfma_f32_16x16x32_bf16 v[34:37], v[50:53], v[74:77], 0
	s_waitcnt lgkmcnt(4)
	v_mfma_f32_16x16x32_bf16 v[34:37], v[54:57], v[78:81], v[34:37]
	ds_read_b128 v[50:53], v234 offset:25344
	ds_read_b128 v[54:57], v234 offset:25408
	s_waitcnt lgkmcnt(5)
	v_mfma_f32_16x16x32_bf16 v[38:41], v[58:61], v[74:77], 0
	s_waitcnt lgkmcnt(4)
	v_mfma_f32_16x16x32_bf16 v[38:41], v[62:65], v[78:81], v[38:41]
	ds_read_b128 v[58:61], v234 offset:27648
	ds_read_b128 v[62:65], v234 offset:27712
	s_waitcnt lgkmcnt(5)
	v_mfma_f32_16x16x32_bf16 v[42:45], v[138:141], v[74:77], 0
	s_waitcnt lgkmcnt(4)
	v_mfma_f32_16x16x32_bf16 v[42:45], v[142:145], v[78:81], v[42:45]
	s_waitcnt lgkmcnt(3)
	v_mfma_f32_16x16x32_bf16 v[46:49], v[50:53], v[74:77], 0
	s_waitcnt lgkmcnt(2)
	v_mfma_f32_16x16x32_bf16 v[46:49], v[54:57], v[78:81], v[46:49]
	ds_read_b128 v[50:53], v234 offset:29952
	ds_read_b128 v[54:57], v234 offset:30016
	v_fma_f32 v34, v34, s48, v146
	v_fma_f32 v35, v35, s48, v146
	v_fma_f32 v36, v36, s48, v146
	v_fma_f32 v37, v37, s48, v146
	v_fma_f32 v38, v38, s48, v146
	v_fma_f32 v39, v39, s48, v146
	v_fma_f32 v40, v40, s48, v146
	v_fma_f32 v41, v41, s48, v146
	v_fma_f32 v42, v42, s48, v146
	v_fma_f32 v43, v43, s48, v146
	v_fma_f32 v44, v44, s48, v146
	v_fma_f32 v45, v45, s48, v146
	v_fma_f32 v46, v46, s48, v146
	v_fma_f32 v47, v47, s48, v146
	v_fma_f32 v48, v48, s48, v146
	v_fma_f32 v49, v49, s48, v146
	s_cmp_lg_u32 s76, s72
	s_cbranch_scc1 .Lsb16_nm1_1
	s_lshl_b32 s83, s76, 6
	v_subrev_u32_e32 v146, s83, v239
	v_add_u32_e32 v146, 2, v146
	v_cmp_le_i32_e64 s[28:29], 0, v146
	s_nop 1
	v_cndmask_b32_e64 v34, v213, v34, s[28:29]
	v_cmp_le_i32_e64 s[28:29], 1, v146
	s_nop 1
	v_cndmask_b32_e64 v35, v213, v35, s[28:29]
	v_cmp_le_i32_e64 s[28:29], 2, v146
	s_nop 1
	v_cndmask_b32_e64 v36, v213, v36, s[28:29]
	v_cmp_le_i32_e64 s[28:29], 3, v146
	s_nop 1
	v_cndmask_b32_e64 v37, v213, v37, s[28:29]
	v_cmp_le_i32_e64 s[28:29], 16, v146
	s_nop 1
	v_cndmask_b32_e64 v38, v213, v38, s[28:29]
	v_cmp_le_i32_e64 s[28:29], 17, v146
	s_nop 1
	v_cndmask_b32_e64 v39, v213, v39, s[28:29]
	v_cmp_le_i32_e64 s[28:29], 18, v146
	s_nop 1
	v_cndmask_b32_e64 v40, v213, v40, s[28:29]
	v_cmp_le_i32_e64 s[28:29], 19, v146
	s_nop 1
	v_cndmask_b32_e64 v41, v213, v41, s[28:29]
	v_cmp_le_i32_e64 s[28:29], 32, v146
	s_nop 1
	v_cndmask_b32_e64 v42, v213, v42, s[28:29]
	v_cmp_le_i32_e64 s[28:29], 33, v146
	s_nop 1
	v_cndmask_b32_e64 v43, v213, v43, s[28:29]
	v_cmp_le_i32_e64 s[28:29], 34, v146
	s_nop 1
	v_cndmask_b32_e64 v44, v213, v44, s[28:29]
	v_cmp_le_i32_e64 s[28:29], 35, v146
	s_nop 1
	v_cndmask_b32_e64 v45, v213, v45, s[28:29]
	v_cmp_le_i32_e64 s[28:29], 48, v146
	s_nop 1
	v_cndmask_b32_e64 v46, v213, v46, s[28:29]
	v_cmp_le_i32_e64 s[28:29], 49, v146
	s_nop 1
	v_cndmask_b32_e64 v47, v213, v47, s[28:29]
	v_cmp_le_i32_e64 s[28:29], 50, v146
	s_nop 1
	v_cndmask_b32_e64 v48, v213, v48, s[28:29]
	v_cmp_le_i32_e64 s[28:29], 51, v146
	s_nop 1
	v_cndmask_b32_e64 v49, v213, v49, s[28:29]

.LBB0_2180:
	s_sub_i32 s20, 0x1df1, s70
	s_max_i32 s20, s20, 0
	s_lshr_b32 s38, s20, 6
	s_lshl_b32 s22, s24, 1
	v_readlane_b32 s20, v231, 26
	s_add_u32 s20, s20, s22
	v_readlane_b32 s21, v231, 27
	s_addc_u32 s21, s21, 0
	v_readlane_b32 s28, v231, 28
	v_readlane_b32 s29, v231, 29
	s_add_u32 s22, s28, s22
	s_addc_u32 s23, s29, 0
	s_lshl_b64 s[28:29], s[38:39], 13
	s_add_u32 s30, s20, s28
	s_addc_u32 s31, s21, s29
	s_add_u32 s28, s22, s28
	s_addc_u32 s29, s23, s29
	global_load_dwordx4 v[240:243], v134, s[30:31]
	global_load_dwordx4 v[244:247], v134, s[28:29]
	global_load_dwordx4 v[248:251], v135, s[30:31]
	global_load_dwordx4 v[252:255], v135, s[28:29]
	v_add_u32_e32 v46, s96, v132
	v_mov_b32_e32 v47, 0
	v_lshlrev_b64 v[46:47], 11, v[46:47]
	v_lshl_add_u64 v[46:47], s[42:43], 0, v[46:47]
	v_or_b32_e32 v48, s95, v102
	v_lshlrev_b32_e32 v48, 7, v48
	v_mov_b32_e32 v49, 0
	v_lshl_add_u64 v[46:47], v[46:47], 0, v[48:49]
	v_lshl_add_u64 v[46:47], v[46:47], 0, v[122:123]
	global_load_dwordx4 v[66:69], v[46:47], off offset:32
	global_load_dwordx4 v[70:73], v[46:47], off offset:64
	global_load_dwordx4 v[74:77], v[46:47], off offset:96
	global_load_dwordx4 v[78:81], v[46:47], off
	v_mbcnt_lo_u32_b32 v40, -1, 0
	v_mbcnt_hi_u32_b32 v40, -1, v40
	v_xor_b32_e32 v41, 16, v40
	v_lshlrev_b32_e32 v41, 2, v41
	v_xor_b32_e32 v42, 32, v40
	v_lshlrev_b32_e32 v42, 2, v42
	ds_bpermute_b32 v43, v41, v129
	ds_bpermute_b32 v44, v41, v235
	s_waitcnt lgkmcnt(0)
	v_add_f32_e32 v129, v129, v43
	v_add_f32_e32 v235, v235, v44
	s_nop 0
	ds_bpermute_b32 v43, v42, v129
	ds_bpermute_b32 v44, v42, v235
	s_waitcnt lgkmcnt(0)
	v_add_f32_e32 v129, v129, v43
	v_add_f32_e32 v235, v235, v44
	v_div_scale_f32 v40, s[98:99], v129, v129, v149
	v_rcp_f32_e32 v41, v40
	v_div_scale_f32 v42, vcc, v149, v129, v149
	v_fma_f32 v43, -v40, v41, 1.0
	v_fmac_f32_e32 v41, v43, v41
	v_mul_f32_e32 v43, v42, v41
	v_fma_f32 v38, -v40, v43, v42
	v_fmac_f32_e32 v43, v38, v41
	v_fma_f32 v40, -v40, v43, v42
	v_div_fmas_f32 v40, v40, v41, v43
	v_div_fixup_f32 v38, v40, v129, v149
	v_div_scale_f32 v40, s[98:99], v235, v235, v147
	v_rcp_f32_e32 v41, v40
	v_div_scale_f32 v42, vcc, v147, v235, v147
	v_fma_f32 v43, -v40, v41, 1.0
	v_fmac_f32_e32 v41, v43, v41
	v_mul_f32_e32 v43, v42, v41
	v_fma_f32 v44, -v40, v43, v42
	v_fmac_f32_e32 v43, v44, v41
	v_fma_f32 v40, -v40, v43, v42
	v_div_fmas_f32 v40, v40, v41, v43
	v_div_fixup_f32 v44, v40, v235, v147
	ds_read2_b32 v[50:51], v237 offset0:0 offset1:1
	ds_read2_b32 v[52:53], v237 offset0:2 offset1:3
	ds_read2_b32 v[54:55], v237 offset0:16 offset1:17
	ds_read2_b32 v[56:57], v237 offset0:18 offset1:19
	ds_read2_b32 v[58:59], v237 offset0:32 offset1:33
	ds_read2_b32 v[60:61], v237 offset0:34 offset1:35
	ds_read2_b32 v[62:63], v237 offset0:48 offset1:49
	ds_read2_b32 v[64:65], v237 offset0:50 offset1:51
	s_waitcnt lgkmcnt(7)
	v_pk_fma_f32 v[50:51], v[2:3], v[38:39], v[50:51] op_sel_hi:[1,0,1]
	s_waitcnt lgkmcnt(6)
	v_pk_fma_f32 v[52:53], v[4:5], v[38:39], v[52:53] op_sel_hi:[1,0,1]
	s_waitcnt lgkmcnt(5)
	v_pk_fma_f32 v[54:55], v[6:7], v[38:39], v[54:55] op_sel_hi:[1,0,1]
	s_waitcnt lgkmcnt(4)
	v_pk_fma_f32 v[56:57], v[8:9], v[38:39], v[56:57] op_sel_hi:[1,0,1]
	s_waitcnt lgkmcnt(3)
	v_pk_fma_f32 v[58:59], v[10:11], v[38:39], v[58:59] op_sel_hi:[1,0,1]
	s_waitcnt lgkmcnt(2)
	v_pk_fma_f32 v[60:61], v[12:13], v[38:39], v[60:61] op_sel_hi:[1,0,1]
	s_waitcnt lgkmcnt(1)
	v_pk_fma_f32 v[62:63], v[14:15], v[38:39], v[62:63] op_sel_hi:[1,0,1]
	s_waitcnt lgkmcnt(0)
	v_pk_fma_f32 v[64:65], v[16:17], v[38:39], v[64:65] op_sel_hi:[1,0,1]
	ds_write2_b32 v237, v50, v51 offset0:0 offset1:1
	ds_write2_b32 v237, v52, v53 offset0:2 offset1:3
	ds_write2_b32 v237, v54, v55 offset0:16 offset1:17
	ds_write2_b32 v237, v56, v57 offset0:18 offset1:19
	ds_write2_b32 v237, v58, v59 offset0:32 offset1:33
	ds_write2_b32 v237, v60, v61 offset0:34 offset1:35
	ds_write2_b32 v237, v62, v63 offset0:48 offset1:49
	ds_write2_b32 v237, v64, v65 offset0:50 offset1:51
	ds_read2_b32 v[50:51], v238 offset0:0 offset1:1
	ds_read2_b32 v[52:53], v238 offset0:2 offset1:3
	ds_read2_b32 v[54:55], v238 offset0:16 offset1:17
	ds_read2_b32 v[56:57], v238 offset0:18 offset1:19
	ds_read2_b32 v[58:59], v238 offset0:32 offset1:33
	ds_read2_b32 v[60:61], v238 offset0:34 offset1:35
	ds_read2_b32 v[62:63], v238 offset0:48 offset1:49
	ds_read2_b32 v[64:65], v238 offset0:50 offset1:51
	s_waitcnt lgkmcnt(7)
	v_pk_fma_f32 v[50:51], v[18:19], v[44:45], v[50:51] op_sel_hi:[1,0,1]
	s_waitcnt lgkmcnt(6)
	v_pk_fma_f32 v[52:53], v[20:21], v[44:45], v[52:53] op_sel_hi:[1,0,1]
	s_waitcnt lgkmcnt(5)
	v_pk_fma_f32 v[54:55], v[22:23], v[44:45], v[54:55] op_sel_hi:[1,0,1]
	s_waitcnt lgkmcnt(4)
	v_pk_fma_f32 v[56:57], v[24:25], v[44:45], v[56:57] op_sel_hi:[1,0,1]
	s_waitcnt lgkmcnt(3)
	v_pk_fma_f32 v[58:59], v[26:27], v[44:45], v[58:59] op_sel_hi:[1,0,1]
	s_waitcnt lgkmcnt(2)
	v_pk_fma_f32 v[60:61], v[28:29], v[44:45], v[60:61] op_sel_hi:[1,0,1]
	s_waitcnt lgkmcnt(1)
	v_pk_fma_f32 v[62:63], v[30:31], v[44:45], v[62:63] op_sel_hi:[1,0,1]
	s_waitcnt lgkmcnt(0)
	v_pk_fma_f32 v[64:65], v[32:33], v[44:45], v[64:65] op_sel_hi:[1,0,1]
	ds_write2_b32 v238, v50, v51 offset0:0 offset1:1
	ds_write2_b32 v238, v52, v53 offset0:2 offset1:3
	ds_write2_b32 v238, v54, v55 offset0:16 offset1:17
	ds_write2_b32 v238, v56, v57 offset0:18 offset1:19
	ds_write2_b32 v238, v58, v59 offset0:32 offset1:33
	ds_write2_b32 v238, v60, v61 offset0:34 offset1:35
	ds_write2_b32 v238, v62, v63 offset0:48 offset1:49
	ds_write2_b32 v238, v64, v65 offset0:50 offset1:51
	s_sub_i32 s25, s72, s38
	v_mov_b32_e32 v34, 0
	v_mov_b32_e32 v35, 0
	v_mov_b32_e32 v36, 0
	v_mov_b32_e32 v37, 0
	v_mov_b32_e32 v38, 0
	v_mov_b32_e32 v39, 0
	v_mov_b32_e32 v40, 0
	v_mov_b32_e32 v41, 0
	v_mov_b32_e32 v42, 0
	v_mov_b32_e32 v43, 0
	v_mov_b32_e32 v44, 0
	v_mov_b32_e32 v45, 0
	v_mov_b32_e32 v46, 0
	v_mov_b32_e32 v47, 0
	v_mov_b32_e32 v48, 0
	v_mov_b32_e32 v49, 0
	v_mov_b32_e32 v50, 0
	v_mov_b32_e32 v51, 0
	v_mov_b32_e32 v52, 0
	v_mov_b32_e32 v53, 0
	v_mov_b32_e32 v54, 0
	v_mov_b32_e32 v55, 0
	v_mov_b32_e32 v56, 0
	v_mov_b32_e32 v57, 0
	v_mov_b32_e32 v58, 0
	v_mov_b32_e32 v59, 0
	v_mov_b32_e32 v60, 0
	v_mov_b32_e32 v61, 0
	v_mov_b32_e32 v62, 0
	v_mov_b32_e32 v63, 0
	v_mov_b32_e32 v64, 0
	v_mov_b32_e32 v65, 0
	v_mov_b32_e32 v129, 0
	s_cmp_lt_i32 s25, 0
	s_cbranch_scc1 .LBB0_2196
	s_cmp_eq_u32 s72, s38
	s_waitcnt vmcnt(0)
	ds_write_b128 v153, v[240:243]
	ds_write_b128 v153, v[244:247] offset:9216
	ds_write_b128 v155, v[248:251]
	ds_write_b128 v155, v[252:255] offset:9216
	s_cbranch_scc1 .LBB0_2185
	s_branch .Lsb16_w2184

.Lsb16_w2184:
	s_add_i32 s38, s38, 1
	s_lshl_b64 s[28:29], s[38:39], 13
	s_add_u32 s30, s20, s28
	s_addc_u32 s31, s21, s29
	s_add_u32 s28, s22, s28
	s_addc_u32 s29, s23, s29
	v_lshl_add_u64 v[2:3], s[30:31], 0, v[128:129]
	v_lshl_add_u64 v[4:5], v[2:3], 0, v[106:107]
	v_lshl_add_u64 v[6:7], s[28:29], 0, v[128:129]
	v_lshl_add_u64 v[2:3], v[2:3], 0, v[108:109]
	v_lshl_add_u64 v[8:9], v[6:7], 0, v[106:107]
	global_load_dwordx4 v[82:85], v[4:5], off
	global_load_dwordx4 v[86:89], v[8:9], off
	v_lshl_add_u64 v[4:5], v[6:7], 0, v[108:109]
	global_load_dwordx4 v[90:93], v[2:3], off
	global_load_dwordx4 v[94:97], v[4:5], off
